# attention loop: hipcc's packed v_pk_add_f32 row-sum adds split into scalar v_add_f32 pairs (bit-identical)
# speedup vs baseline: 1.0088x; 1.0073x over previous
; #define LAS __attribute__((address_space(3)))
; __device__ __forceinline__ float ex2(float x) { return __builtin_amdgcn_exp2f(x); }
; template <bool SAFE>
; __device__ void phase_attn(const Params& p, const bf16_t* Qall, const bf16_t* Kall, const bf16_t* Vt, bf16_t* CAT, LAS unsigned char* lds) {
;     ...
;       for (int c = 0; c < 6; ++c) {
;         const bf16x8 ka = *(const LAS bf16x8*)(kb_ + (r * KROW + 16 * c + 8 * hh) * 2);
;         const bf16x8 kb2 = *(const LAS bf16x8*)(kb_ + ((32 + r) * KROW + 16 * c + 8 * hh) * 2);
; #pragma unroll
;         for (int qb = 0; qb < 2; ++qb) {
;           s[qb][0] = __builtin_amdgcn_mfma_f32_32x32x16_bf16(ka, qf[qb][c], s[qb][0], 0, 0, 0);
;           s[qb][1] = __builtin_amdgcn_mfma_f32_32x32x16_bf16(kb2, qf[qb][c], s[qb][1], 0, 0, 0);
;         }
;       }
; #pragma unroll
;       for (int qb = 0; qb < 2; ++qb) {
;         if (SAFE) {
;           float mx = fmaxf(s[qb][0][0], s[qb][1][0]);
; #pragma unroll
;           for (int e = 1; e < 16; ++e) mx = fmaxf(mx, fmaxf(s[qb][0][e], s[qb][1][e]));
;           mx = fmaxf(mx, __shfl_xor(mx, 32));
;           const bool need = (i == 0) || (mx - mrun[qb] > 8.f);
;           if (__builtin_amdgcn_ballot_w64(need) != 0ull) {
;             const float nm = need ? mx : mrun[qb];
;             const float alpha = (i == 0) ? 1.f : ex2(mrun[qb] - nm);
;             mrun[qb] = nm; lrun[qb] *= alpha;
; #pragma unroll
;             for (int e = 0; e < 16; ++e) { o[qb][0][e] *= alpha; o[qb][1][e] *= alpha; }
;           }
;         }
;         f32x2 ps2 = {0.f, 0.f};
;         const f32x2 m2 = {mrun[qb], mrun[qb]};
; #pragma unroll
;         for (int kb = 0; kb < 2; ++kb)
; #pragma unroll
;           for (int e = 0; e < 16; e += 2) {
;             f32x2 t = {s[qb][kb][e], s[qb][kb][e + 1]};
;             if (SAFE) t = t - m2;
;             t.x = ex2(t.x); t.y = ex2(t.y);
;             ps2 += t;
;             s[qb][kb][e] = t.x; s[qb][kb][e + 1] = t.y;
;           }
;         lrun[qb] += ps2.x + ps2.y;
.LBB0_1258:
	s_bitcmp1_b32 s51, 0
	s_cselect_b32 s28, 0x5800, 0
	s_add_i32 s28, s28, 0
	v_add_u32_e32 v186, s28, v179
	ds_read_b128 v[64:67], v186
	ds_read_b128 v[206:209], v186 offset:32
	ds_read_b128 v[68:71], v186 offset:6656
	ds_read_b128 v[210:213], v186 offset:6688
	s_mov_b32 s51, s50
	s_waitcnt lgkmcnt(0)
	v_mfma_f32_32x32x16_bf16 v[112:127], v[64:67], v[164:167], 0
	v_mfma_f32_32x32x16_bf16 v[96:111], v[68:71], v[164:167], 0
	v_mfma_f32_32x32x16_bf16 v[80:95], v[64:67], v[172:175], 0
	v_mfma_f32_32x32x16_bf16 v[64:79], v[68:71], v[172:175], 0
	v_mfma_f32_32x32x16_bf16 v[112:127], v[206:209], v[160:163], v[112:127]
	v_mfma_f32_32x32x16_bf16 v[96:111], v[210:213], v[160:163], v[96:111]
	v_mfma_f32_32x32x16_bf16 v[80:95], v[206:209], v[168:171], v[80:95]
	v_mfma_f32_32x32x16_bf16 v[64:79], v[210:213], v[168:171], v[64:79]
	ds_read_b128 v[206:209], v186 offset:64
	ds_read_b128 v[210:213], v186 offset:96
	ds_read_b128 v[214:217], v186 offset:6720
	ds_read_b128 v[218:221], v186 offset:6752
	s_waitcnt lgkmcnt(0)
	v_mfma_f32_32x32x16_bf16 v[112:127], v[206:209], v[152:155], v[112:127]
	v_mfma_f32_32x32x16_bf16 v[112:127], v[210:213], v[148:151], v[112:127]
	v_mfma_f32_32x32x16_bf16 v[96:111], v[214:217], v[152:155], v[96:111]
	v_mfma_f32_32x32x16_bf16 v[80:95], v[206:209], v[156:159], v[80:95]
	v_mfma_f32_32x32x16_bf16 v[64:79], v[214:217], v[156:159], v[64:79]
	ds_read_b128 v[206:209], v186 offset:128
	ds_read_b128 v[214:217], v186 offset:160
	ds_read_b128 v[222:225], v186 offset:6784
	ds_read_b128 v[226:229], v186 offset:6816
	s_waitcnt lgkmcnt(0)
	v_mfma_f32_32x32x16_bf16 v[112:127], v[206:209], v[144:147], v[112:127]
	v_mfma_f32_32x32x16_bf16 v[96:111], v[218:221], v[148:151], v[96:111]
	v_mfma_f32_32x32x16_bf16 v[112:127], v[214:217], v[140:143], v[112:127]
	v_mfma_f32_32x32x16_bf16 v[96:111], v[222:225], v[144:147], v[96:111]
	s_nop 10
	v_exp_f32_e32 v230, v112
	v_exp_f32_e32 v231, v113
	v_exp_f32_e32 v232, v114
	v_exp_f32_e32 v233, v115
	v_exp_f32_e32 v234, v116
	v_exp_f32_e32 v235, v117
	v_exp_f32_e32 v236, v118
	v_mfma_f32_32x32x16_bf16 v[80:95], v[210:213], v[136:139], v[80:95]
	v_exp_f32_e32 v237, v119
	v_add_f32_e32 v112, 0, v230
	v_add_f32_e32 v113, 0, v231
	v_exp_f32_e32 v238, v120
	v_exp_f32_e32 v239, v121
	v_add_f32_e32 v112, v232, v112
	v_add_f32_e32 v113, v233, v113
	v_exp_f32_e32 v240, v122
	v_exp_f32_e32 v241, v123
	v_mfma_f32_32x32x16_bf16 v[96:111], v[226:229], v[140:143], v[96:111]
	v_add_f32_e64 v112, v234, v112
	v_add_f32_e64 v113, v235, v113
	v_exp_f32_e32 v124, v124
	v_exp_f32_e32 v125, v125
	v_add_f32_e32 v112, v236, v112
	v_add_f32_e32 v113, v237, v113
	v_exp_f32_e32 v126, v126
	v_add_f32_e32 v112, v238, v112
	v_add_f32_e32 v113, v239, v113
	v_exp_f32_e32 v127, v127
	v_mfma_f32_32x32x16_bf16 v[80:95], v[206:209], v[132:135], v[80:95]
	v_add_f32_e64 v112, v240, v112
	v_add_f32_e64 v113, v241, v113
	s_nop 0
	v_exp_f32_e32 v114, v98
	v_add_f32_e32 v118, v124, v112
	v_add_f32_e32 v119, v125, v113
	v_exp_f32_e32 v112, v96
	v_exp_f32_e32 v113, v97
	v_exp_f32_e32 v115, v99
	v_exp_f32_e32 v116, v100
	v_exp_f32_e32 v117, v101
	v_add_f32_e32 v96, v126, v118
	v_add_f32_e32 v97, v127, v119
	v_mfma_f32_32x32x16_bf16 v[80:95], v[214:217], v[128:131], v[80:95]
	v_add_f32_e64 v96, v112, v96
	v_add_f32_e64 v97, v113, v97
	v_exp_f32_e32 v118, v102
	v_add_f32_e32 v96, v114, v96
	v_add_f32_e32 v97, v115, v97
	v_exp_f32_e32 v119, v103
	v_add_f32_e32 v120, v116, v96
	v_add_f32_e32 v121, v117, v97
	v_exp_f32_e32 v96, v104
	v_exp_f32_e32 v97, v105
	v_mfma_f32_32x32x16_bf16 v[64:79], v[218:221], v[136:139], v[64:79]
	v_exp_f32_e32 v98, v106
	v_exp_f32_e32 v99, v107
	v_exp_f32_e32 v100, v108
	v_exp_f32_e32 v101, v109
	v_add_f32_e32 v102, v118, v120
	v_add_f32_e32 v103, v119, v121
	v_exp_f32_e32 v206, v82
	v_add_f32_e32 v102, v96, v102
	v_add_f32_e32 v103, v97, v103
	v_exp_f32_e32 v207, v83
	v_add_f32_e32 v102, v98, v102
	v_add_f32_e32 v103, v99, v103
	v_mfma_f32_32x32x16_bf16 v[64:79], v[222:225], v[132:135], v[64:79]
	v_add_f32_e64 v104, v100, v102
	v_add_f32_e64 v105, v101, v103
	v_exp_f32_e32 v102, v110
	v_exp_f32_e32 v103, v111
	v_exp_f32_e32 v110, v80
	v_exp_f32_e32 v111, v81
	v_exp_f32_e32 v208, v84
	v_exp_f32_e32 v209, v85
	v_exp_f32_e32 v210, v86
	v_add_f32_e32 v80, 0, v110
	v_add_f32_e32 v81, 0, v111
	v_add_u32_e32 v86, s28, v196
	v_add_f32_e32 v80, v206, v80
	v_add_f32_e32 v81, v207, v81
	v_add_u32_e32 v86, 0x3000, v86
	v_add_f32_e32 v84, v208, v80
	v_add_f32_e32 v85, v209, v81
	v_add_u32_e32 v80, s28, v191
	v_add_u32_e32 v80, 0x3000, v80
	ds_read2_b64 v[80:83], v80 offset0:128 offset1:130
	ds_read2_b64 v[106:109], v86 offset0:128 offset1:130
	v_mfma_f32_32x32x16_bf16 v[64:79], v[226:229], v[128:131], v[64:79]
	v_exp_f32_e32 v211, v87
	v_exp_f32_e32 v212, v88
	v_exp_f32_e32 v213, v89
	v_exp_f32_e32 v214, v90
	v_exp_f32_e32 v215, v91
	v_add_f32_e32 v84, v210, v84
	v_add_f32_e32 v85, v211, v85
	v_cvt_pk_bf16_f32 v120, v230, v231
	v_cvt_pk_bf16_f32 v121, v232, v233
	v_cvt_pk_bf16_f32 v122, v234, v235
	v_cvt_pk_bf16_f32 v123, v236, v237
	v_add_f32_e32 v84, v212, v84
	v_add_f32_e32 v85, v213, v85
	v_cvt_pk_bf16_f32 v86, v208, v209
	s_waitcnt lgkmcnt(0)
; __device__ __forceinline__ unsigned pk2(float lo, float hi) { f32x2 v = {lo, hi}; return __builtin_bit_cast(unsigned, __builtin_convertvector(v, bf16v2)); }
; #define LAS __attribute__((address_space(3)))
; __device__ __forceinline__ float ex2(float x) { return __builtin_amdgcn_exp2f(x); }
; template <bool SAFE>
; __device__ void phase_attn(const Params& p, const bf16_t* Qall, const bf16_t* Kall, const bf16_t* Vt, bf16_t* CAT, LAS unsigned char* lds) {
;     ...
;         f32x2 ps2 = {0.f, 0.f};
;         const f32x2 m2 = {mrun[qb], mrun[qb]};
; #pragma unroll
;         for (int kb = 0; kb < 2; ++kb)
; #pragma unroll
;           for (int e = 0; e < 16; e += 2) {
;             f32x2 t = {s[qb][kb][e], s[qb][kb][e + 1]};
;             if (SAFE) t = t - m2;
;             t.x = ex2(t.x); t.y = ex2(t.y);
;             ps2 += t;
;             s[qb][kb][e] = t.x; s[qb][kb][e + 1] = t.y;
;           }
;         lrun[qb] += ps2.x + ps2.y;
;         if (!SAFE) wbad = wbad || !(ps2.x + ps2.y < 1.2089258e24f);
;       }
; #pragma unroll
;       for (int kb = 0; kb < 2; ++kb)
; #pragma unroll
;         for (int t = 0; t < 2; ++t) {
;           const int kofs = 32 * kb + 16 * t + 4 * hh;
;           u32x4 va, vb2;
;           { const u32x2 lo = *(const LAS u32x2*)(vb_ + (r * VROW + kofs) * 2), hi = *(const LAS u32x2*)(vb_ + (r * VROW + kofs + 8) * 2); va.x = lo.x; va.y = lo.y; va.z = hi.x; va.w = hi.y; }
;           { const u32x2 lo = *(const LAS u32x2*)(vb_ + ((32 + r) * VROW + kofs) * 2), hi = *(const LAS u32x2*)(vb_ + ((32 + r) * VROW + kofs + 8) * 2); vb2.x = lo.x; vb2.y = lo.y; vb2.z = hi.x; vb2.w = hi.y; }
; #pragma unroll
;           for (int qb = 0; qb < 2; ++qb) {
;             u32x4 pw;
;             pw.x = pk2(s[qb][kb][8 * t], s[qb][kb][8 * t + 1]); pw.y = pk2(s[qb][kb][8 * t + 2], s[qb][kb][8 * t + 3]);
;             pw.z = pk2(s[qb][kb][8 * t + 4], s[qb][kb][8 * t + 5]); pw.w = pk2(s[qb][kb][8 * t + 6], s[qb][kb][8 * t + 7]);
;             const bf16x8 pf = __builtin_bit_cast(bf16x8, pw);
;             o[qb][0] = __builtin_amdgcn_mfma_f32_32x32x16_bf16(__builtin_bit_cast(bf16x8, va), pf, o[qb][0], 0, 0, 0);
;             o[qb][1] = __builtin_amdgcn_mfma_f32_32x32x16_bf16(__builtin_bit_cast(bf16x8, vb2), pf, o[qb][1], 0, 0, 0);
;           }
;         }
;       asm volatile("s_waitcnt vmcnt(0)" ::: "memory");
;       __syncthreads();
	v_mfma_f32_32x32x16_bf16 v[48:63], v[80:83], v[120:123], v[48:63]
	v_cvt_pk_bf16_f32 v87, v210, v211
	v_exp_f32_e32 v92, v92
	v_exp_f32_e32 v93, v93
	v_exp_f32_e32 v94, v94
	v_exp_f32_e32 v95, v95
	v_cvt_pk_bf16_f32 v88, v238, v239
	v_cvt_pk_bf16_f32 v89, v240, v241
	v_mfma_f32_32x32x16_bf16 v[32:47], v[106:109], v[120:123], v[32:47]
	v_add_f32_e64 v120, v214, v84
	v_add_f32_e64 v121, v215, v85
	v_cvt_pk_bf16_f32 v84, v110, v111
	v_exp_f32_e32 v110, v64
	v_add_u32_e32 v64, s28, v197
	v_cvt_pk_bf16_f32 v85, v206, v207
	v_add_u32_e32 v64, 0x3000, v64
	v_exp_f32_e32 v111, v65
	v_mfma_f32_32x32x16_bf16 v[16:31], v[80:83], v[84:87], v[16:31]
	ds_read2_b64 v[80:83], v64 offset0:128 offset1:130
	v_add_u32_e32 v64, s28, v198
	v_add_u32_e32 v64, 0x3000, v64
	v_cvt_pk_bf16_f32 v90, v124, v125
	v_cvt_pk_bf16_f32 v91, v126, v127
	v_add_f32_e32 v104, v102, v104
	v_add_f32_e32 v105, v103, v105
	v_mfma_f32_32x32x16_bf16 v[0:15], v[106:109], v[84:87], v[0:15]
	ds_read2_b64 v[84:87], v64 offset0:128 offset1:130
	v_exp_f32_e32 v106, v66
	v_exp_f32_e32 v107, v67
	v_add_f32_e32 v64, v92, v120
	v_add_f32_e32 v65, v93, v121
	v_exp_f32_e32 v120, v68
	v_exp_f32_e32 v121, v69
	v_add_f32_e32 v64, v94, v64
	v_add_f32_e32 v65, v95, v65
	s_waitcnt lgkmcnt(0)
	v_mfma_f32_32x32x16_bf16 v[48:63], v[80:83], v[88:91], v[48:63]
	v_add_f32_e64 v64, v110, v64
	v_add_f32_e64 v65, v111, v65
	v_cvt_pk_bf16_f32 v66, v92, v93
	v_add_f32_e64 v108, v106, v64
	v_add_f32_e64 v109, v107, v65
	v_cvt_pk_bf16_f32 v64, v212, v213
	v_add_f32_e32 v68, v120, v108
	v_add_f32_e32 v69, v121, v109
	v_cvt_pk_bf16_f32 v65, v214, v215
	v_cvt_pk_bf16_f32 v67, v94, v95
	v_mfma_f32_32x32x16_bf16 v[32:47], v[84:87], v[88:91], v[32:47]
	v_exp_f32_e32 v88, v70
	v_exp_f32_e32 v89, v71
	v_exp_f32_e32 v92, v72
	v_exp_f32_e32 v93, v73
	v_add_f32_e32 v90, v88, v68
	v_add_f32_e32 v91, v89, v69
	v_add_u32_e32 v68, s28, v199
	v_mfma_f32_32x32x16_bf16 v[16:31], v[80:83], v[64:67], v[16:31]
	v_add_u32_e32 v68, 0x3000, v68
	ds_read2_b64 v[68:71], v68 offset0:128 offset1:130
	v_add_f32_e64 v72, v92, v90
	v_add_f32_e64 v73, v93, v91
	v_exp_f32_e32 v90, v78
	v_exp_f32_e32 v91, v79
	v_cvt_pk_bf16_f32 v80, v112, v113
	v_cvt_pk_bf16_f32 v81, v114, v115
	v_mfma_f32_32x32x16_bf16 v[0:15], v[84:87], v[64:67], v[0:15]
	v_add_u32_e32 v64, s28, v200
	v_add_u32_e32 v64, 0x3000, v64
	ds_read2_b64 v[64:67], v64 offset0:128 offset1:130
	v_exp_f32_e32 v84, v74
	v_exp_f32_e32 v85, v75
	v_exp_f32_e32 v86, v76
	v_exp_f32_e32 v87, v77
	v_cvt_pk_bf16_f32 v82, v116, v117
	v_add_f32_e32 v72, v84, v72
	v_add_f32_e32 v73, v85, v73
	v_cvt_pk_bf16_f32 v83, v118, v119
	v_add_f32_e32 v72, v86, v72
	v_add_f32_e32 v73, v87, v73
	v_cvt_pk_bf16_f32 v74, v120, v121
	v_add_f32_e32 v76, v90, v72
	v_add_f32_e32 v77, v91, v73
	v_cvt_pk_bf16_f32 v72, v110, v111
	v_cvt_pk_bf16_f32 v73, v106, v107
	v_cvt_pk_bf16_f32 v75, v88, v89
	s_waitcnt lgkmcnt(0)
	v_mfma_f32_32x32x16_bf16 v[48:63], v[68:71], v[80:83], v[48:63]
	v_cvt_pk_bf16_f32 v78, v86, v87
	v_cvt_pk_bf16_f32 v79, v90, v91
	v_mfma_f32_32x32x16_bf16 v[16:31], v[68:71], v[72:75], v[16:31]
	v_mov_b32_e32 v68, v76
	v_mov_b32_e32 v69, v104
	v_mov_b32_e32 v104, v77
	v_add_f32_e64 v76, v68, v104
	v_add_f32_e64 v77, v69, v105
	v_add_u32_e32 v68, s28, v201
	v_add_u32_e32 v68, 0x3000, v68
	ds_read2_b64 v[68:71], v68 offset0:128 offset1:130
	v_mfma_f32_32x32x16_bf16 v[32:47], v[64:67], v[80:83], v[32:47]
	v_cmp_ngt_f32_e32 vcc, s44, v77
	v_add_f32_e64 v194, v194, v76
	v_add_f32_e64 v195, v195, v77
	v_cvt_pk_bf16_f32 v77, v84, v85
	v_mfma_f32_32x32x16_bf16 v[0:15], v[64:67], v[72:75], v[0:15]
	v_add_u32_e32 v64, s28, v202
	v_add_u32_e32 v64, 0x3000, v64
	ds_read2_b64 v[64:67], v64 offset0:128 offset1:130
	v_cvt_pk_bf16_f32 v72, v96, v97
	v_cvt_pk_bf16_f32 v73, v98, v99
	v_cvt_pk_bf16_f32 v74, v100, v101
	v_cvt_pk_bf16_f32 v75, v102, v103
	s_or_b64 s[28:29], s[26:27], vcc
	v_cmp_ngt_f32_e32 vcc, s44, v76
	v_cvt_pk_bf16_f32 v76, v92, v93
	s_waitcnt lgkmcnt(0)
	v_mfma_f32_32x32x16_bf16 v[48:63], v[68:71], v[72:75], v[48:63]
	s_or_b64 s[28:29], s[28:29], vcc
	s_add_u32 s4, s4, 0x3000
	s_addc_u32 s5, s5, 0
	s_add_u32 s15, s15, 0x80
	s_waitcnt vmcnt(0)
	s_addc_u32 s49, s49, 0
	s_andn2_b64 s[26:27], s[26:27], exec
	v_mfma_f32_32x32x16_bf16 v[32:47], v[64:67], v[72:75], v[32:47]
	s_and_b64 s[52:53], s[28:29], exec
	s_or_b64 s[26:27], s[26:27], s[52:53]
	s_cmp_eq_u32 s1, s50
	s_waitcnt vmcnt(0)
	s_barrier
	v_mfma_f32_32x32x16_bf16 v[16:31], v[68:71], v[76:79], v[16:31]
	v_mfma_f32_32x32x16_bf16 v[0:15], v[64:67], v[76:79], v[0:15]
	s_cbranch_scc1 .LBB0_1261
